# k33: k31 + attention prologue scan waits relaxed to the logf loads only (scan/bias chain overlaps the K/V/Q loads)
# speedup vs baseline: 1.0040x; 1.0040x over previous
; #define DPP_SHL(v, n) __builtin_bit_cast(float, __builtin_amdgcn_update_dpp(0, __builtin_bit_cast(int, (v)), 0x100 | (n), 0xF, 0xF, true))
; __device__ __forceinline__ float lane0(float v) { return __builtin_bit_cast(float, __builtin_amdgcn_readfirstlane(__builtin_bit_cast(int, v))); }
; __device__ __forceinline__ float suffix_incl(float v, int lane) {
;     v += DPP_SHL(v, 1); v += DPP_SHL(v, 2); v += DPP_SHL(v, 4); v += DPP_SHL(v, 8);
;     const float t1 = __builtin_bit_cast(float, __builtin_amdgcn_readlane(__builtin_bit_cast(int, v), 16)), t2 = __builtin_bit_cast(float, __builtin_amdgcn_readlane(__builtin_bit_cast(int, v), 32)),
;                 t3 = __builtin_bit_cast(float, __builtin_amdgcn_readlane(__builtin_bit_cast(int, v), 48));
;     const int row = lane >> 4;
;     const float add = (row == 0) ? (t1 + t2) + t3 : (row == 1) ? t2 + t3 : (row == 2) ? t3 : 0.f;
;     return v + add;
; }
; __device__ __forceinline__ void attn_unit(const UnitDesc& u, LAS unsigned char* shm, float qkmax, float thresh) {
;     ...
;     float carry = 0.f, Rown = 0.f, Rq0 = 0.f, inc4[4];
; #pragma unroll
;     for (int i = 0; i < 4; ++i) inc4[i] = suffix_incl(lfb[i], lane);
; #pragma unroll
;     for (int i = 0; i < 4; ++i) { if (i < nband) { const int jb = nband - 1 - i; const float R = carry + inc4[i] - lfb[i];
;         const float ro = __shfl(R, 32 * (wid & 1) + r32); if (jb == (wid >> 1)) Rown = ro;
;         if (jb == 0) Rq0 = __shfl(R, 0);
;         carry += lane0(inc4[i]); } }
.LBB0_734:
	v_lshrrev_b32_e32 v0, 4, v137
	v_cmp_ne_u32_e64 s[8:9], 1, v0
	v_cmp_eq_u32_e64 s[10:11], 2, v0
	s_waitcnt vmcnt(9)
	v_add_f32_dpp v0, v14, v14 row_shl:1 row_mask:0xf bank_mask:0xf bound_ctrl:1
	v_cmp_lt_u32_e64 s[6:7], 15, v137
	s_nop 0
	v_add_f32_dpp v0, v0, v0 row_shl:2 row_mask:0xf bank_mask:0xf bound_ctrl:1
	s_nop 1
	v_add_f32_dpp v0, v0, v0 row_shl:4 row_mask:0xf bank_mask:0xf bound_ctrl:1
	s_nop 1
	v_add_f32_dpp v0, v0, v0 row_shl:8 row_mask:0xf bank_mask:0xf bound_ctrl:1
	s_nop 0
	v_readlane_b32 s28, v0, 16
	v_readlane_b32 s70, v0, 32
	v_readlane_b32 s69, v0, 48
	s_and_saveexec_b64 s[12:13], s[6:7]
	s_xor_b64 s[12:13], exec, s[12:13]
	s_cbranch_execz .LBB0_740
	s_and_saveexec_b64 s[64:65], s[8:9]
	s_xor_b64 s[64:65], exec, s[64:65]
	v_mov_b32_e32 v11, s69
	v_cndmask_b32_e64 v11, 0, v11, s[10:11]
	s_andn2_saveexec_b64 s[64:65], s[64:65]
	v_mov_b32_e32 v11, s69
	v_add_f32_e32 v11, s70, v11
	s_or_b64 exec, exec, s[64:65]
.LBB0_740:
	s_andn2_saveexec_b64 s[12:13], s[12:13]
	v_mov_b32_e32 v11, s70
	v_add_f32_e32 v11, s28, v11
	v_add_f32_e32 v11, s69, v11
	s_or_b64 exec, exec, s[12:13]
	s_waitcnt vmcnt(8)
	v_add_f32_dpp v15, v140, v140 row_shl:1 row_mask:0xf bank_mask:0xf bound_ctrl:1
	s_nop 1
	v_add_f32_dpp v15, v15, v15 row_shl:2 row_mask:0xf bank_mask:0xf bound_ctrl:1
	s_nop 1
	v_add_f32_dpp v15, v15, v15 row_shl:4 row_mask:0xf bank_mask:0xf bound_ctrl:1
	s_nop 1
	v_add_f32_dpp v15, v15, v15 row_shl:8 row_mask:0xf bank_mask:0xf bound_ctrl:1
	s_nop 0
	v_readlane_b32 s28, v15, 16
	v_readlane_b32 s70, v15, 32
	v_readlane_b32 s69, v15, 48
	s_and_saveexec_b64 s[12:13], s[6:7]
	s_xor_b64 s[12:13], exec, s[12:13]
	s_cbranch_execz .LBB0_748
	s_and_saveexec_b64 s[64:65], s[8:9]
	s_xor_b64 s[64:65], exec, s[64:65]
	v_mov_b32_e32 v16, s69
	v_cndmask_b32_e64 v16, 0, v16, s[10:11]
	s_andn2_saveexec_b64 s[64:65], s[64:65]
	v_mov_b32_e32 v16, s69
	v_add_f32_e32 v16, s70, v16
	s_or_b64 exec, exec, s[64:65]
.LBB0_748:
	s_andn2_saveexec_b64 s[12:13], s[12:13]
	v_mov_b32_e32 v16, s70
	v_add_f32_e32 v16, s28, v16
	v_add_f32_e32 v16, s69, v16
	s_or_b64 exec, exec, s[12:13]
	s_waitcnt vmcnt(7)
	v_add_f32_dpp v17, v141, v141 row_shl:1 row_mask:0xf bank_mask:0xf bound_ctrl:1
	s_nop 1
	v_add_f32_dpp v17, v17, v17 row_shl:2 row_mask:0xf bank_mask:0xf bound_ctrl:1
	s_nop 1
	v_add_f32_dpp v17, v17, v17 row_shl:4 row_mask:0xf bank_mask:0xf bound_ctrl:1
	s_nop 1
	v_add_f32_dpp v17, v17, v17 row_shl:8 row_mask:0xf bank_mask:0xf bound_ctrl:1
	s_nop 0
	v_readlane_b32 s28, v17, 16
	v_readlane_b32 s70, v17, 32
	v_readlane_b32 s69, v17, 48
	s_and_saveexec_b64 s[12:13], s[6:7]
	s_xor_b64 s[12:13], exec, s[12:13]
	s_cbranch_execz .LBB0_756
	s_and_saveexec_b64 s[64:65], s[8:9]
	s_xor_b64 s[64:65], exec, s[64:65]
	v_mov_b32_e32 v18, s69
	v_cndmask_b32_e64 v18, 0, v18, s[10:11]
	s_andn2_saveexec_b64 s[64:65], s[64:65]
	v_mov_b32_e32 v18, s69
	v_add_f32_e32 v18, s70, v18
	s_or_b64 exec, exec, s[64:65]
.LBB0_756:
	s_andn2_saveexec_b64 s[12:13], s[12:13]
	v_mov_b32_e32 v18, s70
	v_add_f32_e32 v18, s28, v18
	v_add_f32_e32 v18, s69, v18
	s_or_b64 exec, exec, s[12:13]
	s_waitcnt vmcnt(6)
	v_add_f32_dpp v19, v139, v139 row_shl:1 row_mask:0xf bank_mask:0xf bound_ctrl:1
	s_nop 1
	v_add_f32_dpp v19, v19, v19 row_shl:2 row_mask:0xf bank_mask:0xf bound_ctrl:1
	s_nop 1
	v_add_f32_dpp v19, v19, v19 row_shl:4 row_mask:0xf bank_mask:0xf bound_ctrl:1
	s_nop 1
	v_add_f32_dpp v19, v19, v19 row_shl:8 row_mask:0xf bank_mask:0xf bound_ctrl:1
	s_nop 0
	v_readlane_b32 s28, v19, 16
	v_readlane_b32 s70, v19, 32
	v_readlane_b32 s69, v19, 48
	s_and_saveexec_b64 s[12:13], s[6:7]
	s_xor_b64 s[12:13], exec, s[12:13]
	s_cbranch_execz .LBB0_764
	s_and_saveexec_b64 s[64:65], s[8:9]
	s_xor_b64 s[64:65], exec, s[64:65]
	v_mov_b32_e32 v20, s69
	v_cndmask_b32_e64 v20, 0, v20, s[10:11]
	s_andn2_saveexec_b64 s[64:65], s[64:65]
	v_mov_b32_e32 v20, s69
	v_add_f32_e32 v20, s70, v20
	s_or_b64 exec, exec, s[64:65]
